# grid barrier: XCD leader releases its per-XCD generation word before its own L1 invalidate (on top of the hand-written norm item)
# baseline (speedup 1.0000x reference)
.LBB0_325:
	s_or_b64 exec, exec, s[6:7]
	s_mov_b64 s[6:7], exec
	v_mbcnt_lo_u32_b32 v1, s6, 0
	v_mbcnt_hi_u32_b32 v1, s7, v1
	v_cmp_eq_u32_e32 vcc, 0, v1
	s_waitcnt vmcnt(0)
	s_and_saveexec_b64 s[8:9], vcc
	s_cbranch_execz .LBB0_327
	s_bcnt1_i32_b64 s6, s[6:7]
	v_mov_b32_e32 v2, s6
	v_readlane_b32 s6, v255, 22
	v_mov_b32_e32 v1, 0
	v_readlane_b32 s7, v255, 23
	s_nop 4
	global_atomic_add v1, v2, s[6:7]
.LBB0_327:
	s_or_b64 exec, exec, s[8:9]
	buffer_inv sc1
	s_waitcnt vmcnt(0)

.LBB0_530:
	s_or_b64 exec, exec, s[8:9]
	v_mov_b32_e32 v1, 0x2000
	v_mov_b32_e32 v2, 1
	s_waitcnt vmcnt(0)
	global_atomic_add v1, v2, s[6:7] offset:1024
	buffer_inv sc1
	s_waitcnt vmcnt(0)

.LBB0_733:
	s_or_b64 exec, exec, s[10:11]
	v_mov_b32_e32 v1, 0x2000
	v_mov_b32_e32 v2, 1
	s_waitcnt vmcnt(0)
	global_atomic_add v1, v2, s[8:9] offset:1024
	buffer_inv sc1
	s_waitcnt vmcnt(0)

.LBB0_1188:
	s_or_b64 exec, exec, s[8:9]
	s_mov_b64 s[8:9], exec
	v_mbcnt_lo_u32_b32 v1, s8, 0
	v_mbcnt_hi_u32_b32 v1, s9, v1
	v_cmp_eq_u32_e32 vcc, 0, v1
	s_waitcnt vmcnt(0)
	s_and_saveexec_b64 s[10:11], vcc
	s_cbranch_execz .LBB0_1190
	s_bcnt1_i32_b64 s8, s[8:9]
	v_mov_b32_e32 v2, s8
	v_readlane_b32 s8, v255, 22
	v_mov_b32_e32 v1, 0
	v_readlane_b32 s9, v255, 23
	s_nop 4
	global_atomic_add v1, v2, s[8:9]
.LBB0_1190:
	s_or_b64 exec, exec, s[10:11]
	buffer_inv sc1
	s_waitcnt vmcnt(0)
